# hand-written first row-op phase (f32 inputs -> XB/H): five rows per wave with all loads issued up front, DPP wave sums instead of hipcc's ds_bpermute ladder
# baseline (speedup 1.0000x reference)
.LBB0_131:
.LBB0_132:
	s_mov_b64 s[0:1], exec
	s_lshl_b32 s34, s46, 2
	v_readlane_b32 s10, v164, 0
	s_mov_b32 s11, s46
	v_lshrrev_b32_e32 v80, 6, v128
	v_and_b32_e32 v81, 63, v128
	v_readlane_b32 s16, v163, 13
	v_readlane_b32 s17, v163, 14
	v_readlane_b32 s18, v163, 15
	v_readlane_b32 s19, v163, 16
	v_readlane_b32 s28, v164, 1
	v_readlane_b32 s29, v164, 2
	v_readlane_b32 s30, v164, 3
	v_readlane_b32 s31, v164, 4
	v_readfirstlane_b32 s12, v80
	v_lshlrev_b32_e32 v82, 4, v81
	v_lshlrev_b32_e32 v83, 5, v81
	v_mov_b32_e32 v98, 0x358637bd
	s_lshl_b32 s13, s10, 2
	s_add_u32 s13, s13, s12
	s_lshl_b32 s14, s11, 2
.Lgro0_batch:
	s_mov_b32 s20, s13
	s_min_u32 s21, s20, 0x27ff
	s_sub_u32 s4, s21, 0x2000
	s_cmp_lt_u32 s21, 0x2000
	s_cselect_b32 s4, s21, s4
	s_cselect_b32 s22, s28, s30
	s_cselect_b32 s23, s29, s31
	s_lshl_b32 s4, s4, 12
	s_add_u32 s22, s22, s4
	s_addc_u32 s23, s23, 0
	global_load_dwordx4 v[168:171], v83, s[22:23]
	global_load_dwordx4 v[172:175], v83, s[22:23] offset:16
	global_load_dwordx4 v[176:179], v83, s[22:23] offset:2048
	global_load_dwordx4 v[180:183], v83, s[22:23] offset:2064
	s_add_u32 s20, s20, s14
	s_min_u32 s21, s20, 0x27ff
	s_sub_u32 s4, s21, 0x2000
	s_cmp_lt_u32 s21, 0x2000
	s_cselect_b32 s4, s21, s4
	s_cselect_b32 s22, s28, s30
	s_cselect_b32 s23, s29, s31
	s_lshl_b32 s4, s4, 12
	s_add_u32 s22, s22, s4
	s_addc_u32 s23, s23, 0
	global_load_dwordx4 v[184:187], v83, s[22:23]
	global_load_dwordx4 v[188:191], v83, s[22:23] offset:16
	global_load_dwordx4 v[192:195], v83, s[22:23] offset:2048
	global_load_dwordx4 v[196:199], v83, s[22:23] offset:2064
	s_add_u32 s20, s20, s14
	s_min_u32 s21, s20, 0x27ff
	s_sub_u32 s4, s21, 0x2000
	s_cmp_lt_u32 s21, 0x2000
	s_cselect_b32 s4, s21, s4
	s_cselect_b32 s22, s28, s30
	s_cselect_b32 s23, s29, s31
	s_lshl_b32 s4, s4, 12
	s_add_u32 s22, s22, s4
	s_addc_u32 s23, s23, 0
	global_load_dwordx4 v[200:203], v83, s[22:23]
	global_load_dwordx4 v[204:207], v83, s[22:23] offset:16
	global_load_dwordx4 v[208:211], v83, s[22:23] offset:2048
	global_load_dwordx4 v[212:215], v83, s[22:23] offset:2064
	s_add_u32 s20, s20, s14
	s_min_u32 s21, s20, 0x27ff
	s_sub_u32 s4, s21, 0x2000
	s_cmp_lt_u32 s21, 0x2000
	s_cselect_b32 s4, s21, s4
	s_cselect_b32 s22, s28, s30
	s_cselect_b32 s23, s29, s31
	s_lshl_b32 s4, s4, 12
	s_add_u32 s22, s22, s4
	s_addc_u32 s23, s23, 0
	global_load_dwordx4 v[216:219], v83, s[22:23]
	global_load_dwordx4 v[220:223], v83, s[22:23] offset:16
	global_load_dwordx4 v[224:227], v83, s[22:23] offset:2048
	global_load_dwordx4 v[228:231], v83, s[22:23] offset:2064
	s_add_u32 s20, s20, s14
	s_min_u32 s21, s20, 0x27ff
	s_sub_u32 s4, s21, 0x2000
	s_cmp_lt_u32 s21, 0x2000
	s_cselect_b32 s4, s21, s4
	s_cselect_b32 s22, s28, s30
	s_cselect_b32 s23, s29, s31
	s_lshl_b32 s4, s4, 12
	s_add_u32 s22, s22, s4
	s_addc_u32 s23, s23, 0
	global_load_dwordx4 v[232:235], v83, s[22:23]
	global_load_dwordx4 v[236:239], v83, s[22:23] offset:16
	global_load_dwordx4 v[240:243], v83, s[22:23] offset:2048
	global_load_dwordx4 v[244:247], v83, s[22:23] offset:2064
	s_mov_b32 s15, -1
	s_mov_b32 s20, s13
	s_cmp_ge_u32 s20, 0x2800
	s_cbranch_scc1 .Lgro0_bend
	s_sub_u32 s4, s20, 0x2000
	s_lshr_b32 s4, s4, 10
	s_add_u32 s4, s4, 1
	s_cmp_lt_u32 s20, 0x2000
	s_cselect_b32 s4, 0, s4
	s_cmp_eq_u32 s4, s15
	s_cbranch_scc1 .Lgro0_r0_same
	s_mov_b32 s15, s4
	s_mul_i32 s4, s4, 0x9000
	s_add_u32 s22, s16, s4
	s_addc_u32 s23, s17, 0
	global_load_dwordx4 v[16:19], v83, s[22:23]
	global_load_dwordx4 v[20:23], v83, s[22:23] offset:16
	global_load_dwordx4 v[24:27], v83, s[22:23] offset:2048
	global_load_dwordx4 v[28:31], v83, s[22:23] offset:2064
	s_add_u32 s22, s22, 0x1000
	s_addc_u32 s23, s23, 0
	global_load_dwordx4 v[32:35], v83, s[22:23]
	global_load_dwordx4 v[36:39], v83, s[22:23] offset:16
	global_load_dwordx4 v[40:43], v83, s[22:23] offset:2048
	global_load_dwordx4 v[44:47], v83, s[22:23] offset:2064
	s_waitcnt vmcnt(0)
	s_branch .Lgro0_r0_go

.Lgro0_r0_go:
	s_lshl_b32 s21, s20, 11
	s_add_u32 s22, s86, s21
	s_addc_u32 s23, s87, 0
	v_cvt_pk_bf16_f32 v100, v168, v169
	v_cvt_pk_bf16_f32 v101, v170, v171
	v_cvt_pk_bf16_f32 v102, v172, v173
	v_cvt_pk_bf16_f32 v103, v174, v175
	v_cvt_pk_bf16_f32 v104, v176, v177
	v_cvt_pk_bf16_f32 v105, v178, v179
	v_cvt_pk_bf16_f32 v106, v180, v181
	v_cvt_pk_bf16_f32 v107, v182, v183
	global_store_dwordx4 v82, v[100:103], s[22:23]
	global_store_dwordx4 v82, v[104:107], s[22:23] offset:1024
	v_mul_f32_e32 v88, v168, v168
	v_mul_f32_e32 v89, v169, v169
	v_mul_f32_e32 v90, v170, v170
	v_mul_f32_e32 v91, v171, v171
	v_fmac_f32_e32 v88, v172, v172
	v_fmac_f32_e32 v89, v173, v173
	v_fmac_f32_e32 v90, v174, v174
	v_fmac_f32_e32 v91, v175, v175
	v_fmac_f32_e32 v88, v176, v176
	v_fmac_f32_e32 v89, v177, v177
	v_fmac_f32_e32 v90, v178, v178
	v_fmac_f32_e32 v91, v179, v179
	v_fmac_f32_e32 v88, v180, v180
	v_fmac_f32_e32 v89, v181, v181
	v_fmac_f32_e32 v90, v182, v182
	v_fmac_f32_e32 v91, v183, v183
	v_add_f32_e32 v88, v88, v89
	v_add_f32_e32 v90, v90, v91
	v_add_f32_e32 v84, v88, v90
	s_nop 1
	v_add_f32_dpp v84, v84, v84 quad_perm:[1,0,3,2] row_mask:0xf bank_mask:0xf bound_ctrl:1
	s_nop 1
	v_add_f32_dpp v84, v84, v84 quad_perm:[2,3,0,1] row_mask:0xf bank_mask:0xf bound_ctrl:1
	s_nop 1
	v_add_f32_dpp v84, v84, v84 row_half_mirror row_mask:0xf bank_mask:0xf bound_ctrl:1
	s_nop 1
	v_add_f32_dpp v84, v84, v84 row_mirror row_mask:0xf bank_mask:0xf bound_ctrl:1
	s_nop 0
	v_readlane_b32 s24, v84, 0
	v_readlane_b32 s25, v84, 16
	v_readlane_b32 s26, v84, 32
	v_readlane_b32 s27, v84, 48
	s_nop 0
	v_mov_b32_e32 v85, s24
	v_mov_b32_e32 v86, s26
	v_add_f32_e32 v85, s25, v85
	v_add_f32_e32 v86, s27, v86
	v_add_f32_e32 v84, v85, v86
	v_fmamk_f32 v84, v84, 0x3a800000, v98
	v_rsq_f32_e32 v84, v84
	s_nop 0
	v_mul_f32_e32 v92, v168, v84
	v_fma_f32 v64, v92, v32, v16
	v_mul_f32_e32 v93, v169, v84
	v_fma_f32 v65, v93, v33, v17
	v_mul_f32_e32 v94, v170, v84
	v_fma_f32 v66, v94, v34, v18
	v_mul_f32_e32 v95, v171, v84
	v_fma_f32 v67, v95, v35, v19
	v_mul_f32_e32 v92, v172, v84
	v_fma_f32 v68, v92, v36, v20
	v_mul_f32_e32 v93, v173, v84
	v_fma_f32 v69, v93, v37, v21
	v_mul_f32_e32 v94, v174, v84
	v_fma_f32 v70, v94, v38, v22
	v_mul_f32_e32 v95, v175, v84
	v_fma_f32 v71, v95, v39, v23
	v_mul_f32_e32 v92, v176, v84
	v_fma_f32 v72, v92, v40, v24
	v_mul_f32_e32 v93, v177, v84
	v_fma_f32 v73, v93, v41, v25
	v_mul_f32_e32 v94, v178, v84
	v_fma_f32 v74, v94, v42, v26
	v_mul_f32_e32 v95, v179, v84
	v_fma_f32 v75, v95, v43, v27
	v_mul_f32_e32 v92, v180, v84
	v_fma_f32 v76, v92, v44, v28
	v_mul_f32_e32 v93, v181, v84
	v_fma_f32 v77, v93, v45, v29
	v_mul_f32_e32 v94, v182, v84
	v_fma_f32 v78, v94, v46, v30
	v_mul_f32_e32 v95, v183, v84
	v_fma_f32 v79, v95, v47, v31
	s_add_u32 s22, s18, s21
	s_addc_u32 s23, s19, 0
	v_cvt_pk_bf16_f32 v108, v64, v65
	v_cvt_pk_bf16_f32 v109, v66, v67
	v_cvt_pk_bf16_f32 v110, v68, v69
	v_cvt_pk_bf16_f32 v111, v70, v71
	v_cvt_pk_bf16_f32 v112, v72, v73
	v_cvt_pk_bf16_f32 v113, v74, v75
	v_cvt_pk_bf16_f32 v114, v76, v77
	v_cvt_pk_bf16_f32 v115, v78, v79
	global_store_dwordx4 v82, v[108:111], s[22:23]
	global_store_dwordx4 v82, v[112:115], s[22:23] offset:1024
	s_add_u32 s20, s20, s14
	s_cmp_ge_u32 s20, 0x2800
	s_cbranch_scc1 .Lgro0_bend
	s_sub_u32 s4, s20, 0x2000
	s_lshr_b32 s4, s4, 10
	s_add_u32 s4, s4, 1
	s_cmp_lt_u32 s20, 0x2000
	s_cselect_b32 s4, 0, s4
	s_cmp_eq_u32 s4, s15
	s_cbranch_scc1 .Lgro0_r1_same
	s_mov_b32 s15, s4
	s_mul_i32 s4, s4, 0x9000
	s_add_u32 s22, s16, s4
	s_addc_u32 s23, s17, 0
	global_load_dwordx4 v[16:19], v83, s[22:23]
	global_load_dwordx4 v[20:23], v83, s[22:23] offset:16
	global_load_dwordx4 v[24:27], v83, s[22:23] offset:2048
	global_load_dwordx4 v[28:31], v83, s[22:23] offset:2064
	s_add_u32 s22, s22, 0x1000
	s_addc_u32 s23, s23, 0
	global_load_dwordx4 v[32:35], v83, s[22:23]
	global_load_dwordx4 v[36:39], v83, s[22:23] offset:16
	global_load_dwordx4 v[40:43], v83, s[22:23] offset:2048
	global_load_dwordx4 v[44:47], v83, s[22:23] offset:2064
	s_waitcnt vmcnt(0)
	s_branch .Lgro0_r1_go

.Lgro0_r1_go:
	s_lshl_b32 s21, s20, 11
	s_add_u32 s22, s86, s21
	s_addc_u32 s23, s87, 0
	v_cvt_pk_bf16_f32 v100, v184, v185
	v_cvt_pk_bf16_f32 v101, v186, v187
	v_cvt_pk_bf16_f32 v102, v188, v189
	v_cvt_pk_bf16_f32 v103, v190, v191
	v_cvt_pk_bf16_f32 v104, v192, v193
	v_cvt_pk_bf16_f32 v105, v194, v195
	v_cvt_pk_bf16_f32 v106, v196, v197
	v_cvt_pk_bf16_f32 v107, v198, v199
	global_store_dwordx4 v82, v[100:103], s[22:23]
	global_store_dwordx4 v82, v[104:107], s[22:23] offset:1024
	v_mul_f32_e32 v88, v184, v184
	v_mul_f32_e32 v89, v185, v185
	v_mul_f32_e32 v90, v186, v186
	v_mul_f32_e32 v91, v187, v187
	v_fmac_f32_e32 v88, v188, v188
	v_fmac_f32_e32 v89, v189, v189
	v_fmac_f32_e32 v90, v190, v190
	v_fmac_f32_e32 v91, v191, v191
	v_fmac_f32_e32 v88, v192, v192
	v_fmac_f32_e32 v89, v193, v193
	v_fmac_f32_e32 v90, v194, v194
	v_fmac_f32_e32 v91, v195, v195
	v_fmac_f32_e32 v88, v196, v196
	v_fmac_f32_e32 v89, v197, v197
	v_fmac_f32_e32 v90, v198, v198
	v_fmac_f32_e32 v91, v199, v199
	v_add_f32_e32 v88, v88, v89
	v_add_f32_e32 v90, v90, v91
	v_add_f32_e32 v84, v88, v90
	s_nop 1
	v_add_f32_dpp v84, v84, v84 quad_perm:[1,0,3,2] row_mask:0xf bank_mask:0xf bound_ctrl:1
	s_nop 1
	v_add_f32_dpp v84, v84, v84 quad_perm:[2,3,0,1] row_mask:0xf bank_mask:0xf bound_ctrl:1
	s_nop 1
	v_add_f32_dpp v84, v84, v84 row_half_mirror row_mask:0xf bank_mask:0xf bound_ctrl:1
	s_nop 1
	v_add_f32_dpp v84, v84, v84 row_mirror row_mask:0xf bank_mask:0xf bound_ctrl:1
	s_nop 0
	v_readlane_b32 s24, v84, 0
	v_readlane_b32 s25, v84, 16
	v_readlane_b32 s26, v84, 32
	v_readlane_b32 s27, v84, 48
	s_nop 0
	v_mov_b32_e32 v85, s24
	v_mov_b32_e32 v86, s26
	v_add_f32_e32 v85, s25, v85
	v_add_f32_e32 v86, s27, v86
	v_add_f32_e32 v84, v85, v86
	v_fmamk_f32 v84, v84, 0x3a800000, v98
	v_rsq_f32_e32 v84, v84
	s_nop 0
	v_mul_f32_e32 v92, v184, v84
	v_fma_f32 v64, v92, v32, v16
	v_mul_f32_e32 v93, v185, v84
	v_fma_f32 v65, v93, v33, v17
	v_mul_f32_e32 v94, v186, v84
	v_fma_f32 v66, v94, v34, v18
	v_mul_f32_e32 v95, v187, v84
	v_fma_f32 v67, v95, v35, v19
	v_mul_f32_e32 v92, v188, v84
	v_fma_f32 v68, v92, v36, v20
	v_mul_f32_e32 v93, v189, v84
	v_fma_f32 v69, v93, v37, v21
	v_mul_f32_e32 v94, v190, v84
	v_fma_f32 v70, v94, v38, v22
	v_mul_f32_e32 v95, v191, v84
	v_fma_f32 v71, v95, v39, v23
	v_mul_f32_e32 v92, v192, v84
	v_fma_f32 v72, v92, v40, v24
	v_mul_f32_e32 v93, v193, v84
	v_fma_f32 v73, v93, v41, v25
	v_mul_f32_e32 v94, v194, v84
	v_fma_f32 v74, v94, v42, v26
	v_mul_f32_e32 v95, v195, v84
	v_fma_f32 v75, v95, v43, v27
	v_mul_f32_e32 v92, v196, v84
	v_fma_f32 v76, v92, v44, v28
	v_mul_f32_e32 v93, v197, v84
	v_fma_f32 v77, v93, v45, v29
	v_mul_f32_e32 v94, v198, v84
	v_fma_f32 v78, v94, v46, v30
	v_mul_f32_e32 v95, v199, v84
	v_fma_f32 v79, v95, v47, v31
	s_add_u32 s22, s18, s21
	s_addc_u32 s23, s19, 0
	v_cvt_pk_bf16_f32 v108, v64, v65
	v_cvt_pk_bf16_f32 v109, v66, v67
	v_cvt_pk_bf16_f32 v110, v68, v69
	v_cvt_pk_bf16_f32 v111, v70, v71
	v_cvt_pk_bf16_f32 v112, v72, v73
	v_cvt_pk_bf16_f32 v113, v74, v75
	v_cvt_pk_bf16_f32 v114, v76, v77
	v_cvt_pk_bf16_f32 v115, v78, v79
	global_store_dwordx4 v82, v[108:111], s[22:23]
	global_store_dwordx4 v82, v[112:115], s[22:23] offset:1024
	s_add_u32 s20, s20, s14
	s_cmp_ge_u32 s20, 0x2800
	s_cbranch_scc1 .Lgro0_bend
	s_sub_u32 s4, s20, 0x2000
	s_lshr_b32 s4, s4, 10
	s_add_u32 s4, s4, 1
	s_cmp_lt_u32 s20, 0x2000
	s_cselect_b32 s4, 0, s4
	s_cmp_eq_u32 s4, s15
	s_cbranch_scc1 .Lgro0_r2_same
	s_mov_b32 s15, s4
	s_mul_i32 s4, s4, 0x9000
	s_add_u32 s22, s16, s4
	s_addc_u32 s23, s17, 0
	global_load_dwordx4 v[16:19], v83, s[22:23]
	global_load_dwordx4 v[20:23], v83, s[22:23] offset:16
	global_load_dwordx4 v[24:27], v83, s[22:23] offset:2048
	global_load_dwordx4 v[28:31], v83, s[22:23] offset:2064
	s_add_u32 s22, s22, 0x1000
	s_addc_u32 s23, s23, 0
	global_load_dwordx4 v[32:35], v83, s[22:23]
	global_load_dwordx4 v[36:39], v83, s[22:23] offset:16
	global_load_dwordx4 v[40:43], v83, s[22:23] offset:2048
	global_load_dwordx4 v[44:47], v83, s[22:23] offset:2064
	s_waitcnt vmcnt(0)
	s_branch .Lgro0_r2_go

.Lgro0_r2_go:
	s_lshl_b32 s21, s20, 11
	s_add_u32 s22, s86, s21
	s_addc_u32 s23, s87, 0
	v_cvt_pk_bf16_f32 v100, v200, v201
	v_cvt_pk_bf16_f32 v101, v202, v203
	v_cvt_pk_bf16_f32 v102, v204, v205
	v_cvt_pk_bf16_f32 v103, v206, v207
	v_cvt_pk_bf16_f32 v104, v208, v209
	v_cvt_pk_bf16_f32 v105, v210, v211
	v_cvt_pk_bf16_f32 v106, v212, v213
	v_cvt_pk_bf16_f32 v107, v214, v215
	global_store_dwordx4 v82, v[100:103], s[22:23]
	global_store_dwordx4 v82, v[104:107], s[22:23] offset:1024
	v_mul_f32_e32 v88, v200, v200
	v_mul_f32_e32 v89, v201, v201
	v_mul_f32_e32 v90, v202, v202
	v_mul_f32_e32 v91, v203, v203
	v_fmac_f32_e32 v88, v204, v204
	v_fmac_f32_e32 v89, v205, v205
	v_fmac_f32_e32 v90, v206, v206
	v_fmac_f32_e32 v91, v207, v207
	v_fmac_f32_e32 v88, v208, v208
	v_fmac_f32_e32 v89, v209, v209
	v_fmac_f32_e32 v90, v210, v210
	v_fmac_f32_e32 v91, v211, v211
	v_fmac_f32_e32 v88, v212, v212
	v_fmac_f32_e32 v89, v213, v213
	v_fmac_f32_e32 v90, v214, v214
	v_fmac_f32_e32 v91, v215, v215
	v_add_f32_e32 v88, v88, v89
	v_add_f32_e32 v90, v90, v91
	v_add_f32_e32 v84, v88, v90
	s_nop 1
	v_add_f32_dpp v84, v84, v84 quad_perm:[1,0,3,2] row_mask:0xf bank_mask:0xf bound_ctrl:1
	s_nop 1
	v_add_f32_dpp v84, v84, v84 quad_perm:[2,3,0,1] row_mask:0xf bank_mask:0xf bound_ctrl:1
	s_nop 1
	v_add_f32_dpp v84, v84, v84 row_half_mirror row_mask:0xf bank_mask:0xf bound_ctrl:1
	s_nop 1
	v_add_f32_dpp v84, v84, v84 row_mirror row_mask:0xf bank_mask:0xf bound_ctrl:1
	s_nop 0
	v_readlane_b32 s24, v84, 0
	v_readlane_b32 s25, v84, 16
	v_readlane_b32 s26, v84, 32
	v_readlane_b32 s27, v84, 48
	s_nop 0
	v_mov_b32_e32 v85, s24
	v_mov_b32_e32 v86, s26
	v_add_f32_e32 v85, s25, v85
	v_add_f32_e32 v86, s27, v86
	v_add_f32_e32 v84, v85, v86
	v_fmamk_f32 v84, v84, 0x3a800000, v98
	v_rsq_f32_e32 v84, v84
	s_nop 0
	v_mul_f32_e32 v92, v200, v84
	v_fma_f32 v64, v92, v32, v16
	v_mul_f32_e32 v93, v201, v84
	v_fma_f32 v65, v93, v33, v17
	v_mul_f32_e32 v94, v202, v84
	v_fma_f32 v66, v94, v34, v18
	v_mul_f32_e32 v95, v203, v84
	v_fma_f32 v67, v95, v35, v19
	v_mul_f32_e32 v92, v204, v84
	v_fma_f32 v68, v92, v36, v20
	v_mul_f32_e32 v93, v205, v84
	v_fma_f32 v69, v93, v37, v21
	v_mul_f32_e32 v94, v206, v84
	v_fma_f32 v70, v94, v38, v22
	v_mul_f32_e32 v95, v207, v84
	v_fma_f32 v71, v95, v39, v23
	v_mul_f32_e32 v92, v208, v84
	v_fma_f32 v72, v92, v40, v24
	v_mul_f32_e32 v93, v209, v84
	v_fma_f32 v73, v93, v41, v25
	v_mul_f32_e32 v94, v210, v84
	v_fma_f32 v74, v94, v42, v26
	v_mul_f32_e32 v95, v211, v84
	v_fma_f32 v75, v95, v43, v27
	v_mul_f32_e32 v92, v212, v84
	v_fma_f32 v76, v92, v44, v28
	v_mul_f32_e32 v93, v213, v84
	v_fma_f32 v77, v93, v45, v29
	v_mul_f32_e32 v94, v214, v84
	v_fma_f32 v78, v94, v46, v30
	v_mul_f32_e32 v95, v215, v84
	v_fma_f32 v79, v95, v47, v31
	s_add_u32 s22, s18, s21
	s_addc_u32 s23, s19, 0
	v_cvt_pk_bf16_f32 v108, v64, v65
	v_cvt_pk_bf16_f32 v109, v66, v67
	v_cvt_pk_bf16_f32 v110, v68, v69
	v_cvt_pk_bf16_f32 v111, v70, v71
	v_cvt_pk_bf16_f32 v112, v72, v73
	v_cvt_pk_bf16_f32 v113, v74, v75
	v_cvt_pk_bf16_f32 v114, v76, v77
	v_cvt_pk_bf16_f32 v115, v78, v79
	global_store_dwordx4 v82, v[108:111], s[22:23]
	global_store_dwordx4 v82, v[112:115], s[22:23] offset:1024
	s_add_u32 s20, s20, s14
	s_cmp_ge_u32 s20, 0x2800
	s_cbranch_scc1 .Lgro0_bend
	s_sub_u32 s4, s20, 0x2000
	s_lshr_b32 s4, s4, 10
	s_add_u32 s4, s4, 1
	s_cmp_lt_u32 s20, 0x2000
	s_cselect_b32 s4, 0, s4
	s_cmp_eq_u32 s4, s15
	s_cbranch_scc1 .Lgro0_r3_same
	s_mov_b32 s15, s4
	s_mul_i32 s4, s4, 0x9000
	s_add_u32 s22, s16, s4
	s_addc_u32 s23, s17, 0
	global_load_dwordx4 v[16:19], v83, s[22:23]
	global_load_dwordx4 v[20:23], v83, s[22:23] offset:16
	global_load_dwordx4 v[24:27], v83, s[22:23] offset:2048
	global_load_dwordx4 v[28:31], v83, s[22:23] offset:2064
	s_add_u32 s22, s22, 0x1000
	s_addc_u32 s23, s23, 0
	global_load_dwordx4 v[32:35], v83, s[22:23]
	global_load_dwordx4 v[36:39], v83, s[22:23] offset:16
	global_load_dwordx4 v[40:43], v83, s[22:23] offset:2048
	global_load_dwordx4 v[44:47], v83, s[22:23] offset:2064
	s_waitcnt vmcnt(0)
	s_branch .Lgro0_r3_go

.Lgro0_r3_go:
	s_lshl_b32 s21, s20, 11
	s_add_u32 s22, s86, s21
	s_addc_u32 s23, s87, 0
	v_cvt_pk_bf16_f32 v100, v216, v217
	v_cvt_pk_bf16_f32 v101, v218, v219
	v_cvt_pk_bf16_f32 v102, v220, v221
	v_cvt_pk_bf16_f32 v103, v222, v223
	v_cvt_pk_bf16_f32 v104, v224, v225
	v_cvt_pk_bf16_f32 v105, v226, v227
	v_cvt_pk_bf16_f32 v106, v228, v229
	v_cvt_pk_bf16_f32 v107, v230, v231
	global_store_dwordx4 v82, v[100:103], s[22:23]
	global_store_dwordx4 v82, v[104:107], s[22:23] offset:1024
	v_mul_f32_e32 v88, v216, v216
	v_mul_f32_e32 v89, v217, v217
	v_mul_f32_e32 v90, v218, v218
	v_mul_f32_e32 v91, v219, v219
	v_fmac_f32_e32 v88, v220, v220
	v_fmac_f32_e32 v89, v221, v221
	v_fmac_f32_e32 v90, v222, v222
	v_fmac_f32_e32 v91, v223, v223
	v_fmac_f32_e32 v88, v224, v224
	v_fmac_f32_e32 v89, v225, v225
	v_fmac_f32_e32 v90, v226, v226
	v_fmac_f32_e32 v91, v227, v227
	v_fmac_f32_e32 v88, v228, v228
	v_fmac_f32_e32 v89, v229, v229
	v_fmac_f32_e32 v90, v230, v230
	v_fmac_f32_e32 v91, v231, v231
	v_add_f32_e32 v88, v88, v89
	v_add_f32_e32 v90, v90, v91
	v_add_f32_e32 v84, v88, v90
	s_nop 1
	v_add_f32_dpp v84, v84, v84 quad_perm:[1,0,3,2] row_mask:0xf bank_mask:0xf bound_ctrl:1
	s_nop 1
	v_add_f32_dpp v84, v84, v84 quad_perm:[2,3,0,1] row_mask:0xf bank_mask:0xf bound_ctrl:1
	s_nop 1
	v_add_f32_dpp v84, v84, v84 row_half_mirror row_mask:0xf bank_mask:0xf bound_ctrl:1
	s_nop 1
	v_add_f32_dpp v84, v84, v84 row_mirror row_mask:0xf bank_mask:0xf bound_ctrl:1
	s_nop 0
	v_readlane_b32 s24, v84, 0
	v_readlane_b32 s25, v84, 16
	v_readlane_b32 s26, v84, 32
	v_readlane_b32 s27, v84, 48
	s_nop 0
	v_mov_b32_e32 v85, s24
	v_mov_b32_e32 v86, s26
	v_add_f32_e32 v85, s25, v85
	v_add_f32_e32 v86, s27, v86
	v_add_f32_e32 v84, v85, v86
	v_fmamk_f32 v84, v84, 0x3a800000, v98
	v_rsq_f32_e32 v84, v84
	s_nop 0
	v_mul_f32_e32 v92, v216, v84
	v_fma_f32 v64, v92, v32, v16
	v_mul_f32_e32 v93, v217, v84
	v_fma_f32 v65, v93, v33, v17
	v_mul_f32_e32 v94, v218, v84
	v_fma_f32 v66, v94, v34, v18
	v_mul_f32_e32 v95, v219, v84
	v_fma_f32 v67, v95, v35, v19
	v_mul_f32_e32 v92, v220, v84
	v_fma_f32 v68, v92, v36, v20
	v_mul_f32_e32 v93, v221, v84
	v_fma_f32 v69, v93, v37, v21
	v_mul_f32_e32 v94, v222, v84
	v_fma_f32 v70, v94, v38, v22
	v_mul_f32_e32 v95, v223, v84
	v_fma_f32 v71, v95, v39, v23
	v_mul_f32_e32 v92, v224, v84
	v_fma_f32 v72, v92, v40, v24
	v_mul_f32_e32 v93, v225, v84
	v_fma_f32 v73, v93, v41, v25
	v_mul_f32_e32 v94, v226, v84
	v_fma_f32 v74, v94, v42, v26
	v_mul_f32_e32 v95, v227, v84
	v_fma_f32 v75, v95, v43, v27
	v_mul_f32_e32 v92, v228, v84
	v_fma_f32 v76, v92, v44, v28
	v_mul_f32_e32 v93, v229, v84
	v_fma_f32 v77, v93, v45, v29
	v_mul_f32_e32 v94, v230, v84
	v_fma_f32 v78, v94, v46, v30
	v_mul_f32_e32 v95, v231, v84
	v_fma_f32 v79, v95, v47, v31
	s_add_u32 s22, s18, s21
	s_addc_u32 s23, s19, 0
	v_cvt_pk_bf16_f32 v108, v64, v65
	v_cvt_pk_bf16_f32 v109, v66, v67
	v_cvt_pk_bf16_f32 v110, v68, v69
	v_cvt_pk_bf16_f32 v111, v70, v71
	v_cvt_pk_bf16_f32 v112, v72, v73
	v_cvt_pk_bf16_f32 v113, v74, v75
	v_cvt_pk_bf16_f32 v114, v76, v77
	v_cvt_pk_bf16_f32 v115, v78, v79
	global_store_dwordx4 v82, v[108:111], s[22:23]
	global_store_dwordx4 v82, v[112:115], s[22:23] offset:1024
	s_add_u32 s20, s20, s14
	s_cmp_ge_u32 s20, 0x2800
	s_cbranch_scc1 .Lgro0_bend
	s_sub_u32 s4, s20, 0x2000
	s_lshr_b32 s4, s4, 10
	s_add_u32 s4, s4, 1
	s_cmp_lt_u32 s20, 0x2000
	s_cselect_b32 s4, 0, s4
	s_cmp_eq_u32 s4, s15
	s_cbranch_scc1 .Lgro0_r4_same
	s_mov_b32 s15, s4
	s_mul_i32 s4, s4, 0x9000
	s_add_u32 s22, s16, s4
	s_addc_u32 s23, s17, 0
	global_load_dwordx4 v[16:19], v83, s[22:23]
	global_load_dwordx4 v[20:23], v83, s[22:23] offset:16
	global_load_dwordx4 v[24:27], v83, s[22:23] offset:2048
	global_load_dwordx4 v[28:31], v83, s[22:23] offset:2064
	s_add_u32 s22, s22, 0x1000
	s_addc_u32 s23, s23, 0
	global_load_dwordx4 v[32:35], v83, s[22:23]
	global_load_dwordx4 v[36:39], v83, s[22:23] offset:16
	global_load_dwordx4 v[40:43], v83, s[22:23] offset:2048
	global_load_dwordx4 v[44:47], v83, s[22:23] offset:2064
	s_waitcnt vmcnt(0)
	s_branch .Lgro0_r4_go

.Lgro0_r4_go:
	s_lshl_b32 s21, s20, 11
	s_add_u32 s22, s86, s21
	s_addc_u32 s23, s87, 0
	v_cvt_pk_bf16_f32 v100, v232, v233
	v_cvt_pk_bf16_f32 v101, v234, v235
	v_cvt_pk_bf16_f32 v102, v236, v237
	v_cvt_pk_bf16_f32 v103, v238, v239
	v_cvt_pk_bf16_f32 v104, v240, v241
	v_cvt_pk_bf16_f32 v105, v242, v243
	v_cvt_pk_bf16_f32 v106, v244, v245
	v_cvt_pk_bf16_f32 v107, v246, v247
	global_store_dwordx4 v82, v[100:103], s[22:23]
	global_store_dwordx4 v82, v[104:107], s[22:23] offset:1024
	v_mul_f32_e32 v88, v232, v232
	v_mul_f32_e32 v89, v233, v233
	v_mul_f32_e32 v90, v234, v234
	v_mul_f32_e32 v91, v235, v235
	v_fmac_f32_e32 v88, v236, v236
	v_fmac_f32_e32 v89, v237, v237
	v_fmac_f32_e32 v90, v238, v238
	v_fmac_f32_e32 v91, v239, v239
	v_fmac_f32_e32 v88, v240, v240
	v_fmac_f32_e32 v89, v241, v241
	v_fmac_f32_e32 v90, v242, v242
	v_fmac_f32_e32 v91, v243, v243
	v_fmac_f32_e32 v88, v244, v244
	v_fmac_f32_e32 v89, v245, v245
	v_fmac_f32_e32 v90, v246, v246
	v_fmac_f32_e32 v91, v247, v247
	v_add_f32_e32 v88, v88, v89
	v_add_f32_e32 v90, v90, v91
	v_add_f32_e32 v84, v88, v90
	s_nop 1
	v_add_f32_dpp v84, v84, v84 quad_perm:[1,0,3,2] row_mask:0xf bank_mask:0xf bound_ctrl:1
	s_nop 1
	v_add_f32_dpp v84, v84, v84 quad_perm:[2,3,0,1] row_mask:0xf bank_mask:0xf bound_ctrl:1
	s_nop 1
	v_add_f32_dpp v84, v84, v84 row_half_mirror row_mask:0xf bank_mask:0xf bound_ctrl:1
	s_nop 1
	v_add_f32_dpp v84, v84, v84 row_mirror row_mask:0xf bank_mask:0xf bound_ctrl:1
	s_nop 0
	v_readlane_b32 s24, v84, 0
	v_readlane_b32 s25, v84, 16
	v_readlane_b32 s26, v84, 32
	v_readlane_b32 s27, v84, 48
	s_nop 0
	v_mov_b32_e32 v85, s24
	v_mov_b32_e32 v86, s26
	v_add_f32_e32 v85, s25, v85
	v_add_f32_e32 v86, s27, v86
	v_add_f32_e32 v84, v85, v86
	v_fmamk_f32 v84, v84, 0x3a800000, v98
	v_rsq_f32_e32 v84, v84
	s_nop 0
	v_mul_f32_e32 v92, v232, v84
	v_fma_f32 v64, v92, v32, v16
	v_mul_f32_e32 v93, v233, v84
	v_fma_f32 v65, v93, v33, v17
	v_mul_f32_e32 v94, v234, v84
	v_fma_f32 v66, v94, v34, v18
	v_mul_f32_e32 v95, v235, v84
	v_fma_f32 v67, v95, v35, v19
	v_mul_f32_e32 v92, v236, v84
	v_fma_f32 v68, v92, v36, v20
	v_mul_f32_e32 v93, v237, v84
	v_fma_f32 v69, v93, v37, v21
	v_mul_f32_e32 v94, v238, v84
	v_fma_f32 v70, v94, v38, v22
	v_mul_f32_e32 v95, v239, v84
	v_fma_f32 v71, v95, v39, v23
	v_mul_f32_e32 v92, v240, v84
	v_fma_f32 v72, v92, v40, v24
	v_mul_f32_e32 v93, v241, v84
	v_fma_f32 v73, v93, v41, v25
	v_mul_f32_e32 v94, v242, v84
	v_fma_f32 v74, v94, v42, v26
	v_mul_f32_e32 v95, v243, v84
	v_fma_f32 v75, v95, v43, v27
	v_mul_f32_e32 v92, v244, v84
	v_fma_f32 v76, v92, v44, v28
	v_mul_f32_e32 v93, v245, v84
	v_fma_f32 v77, v93, v45, v29
	v_mul_f32_e32 v94, v246, v84
	v_fma_f32 v78, v94, v46, v30
	v_mul_f32_e32 v95, v247, v84
	v_fma_f32 v79, v95, v47, v31
	s_add_u32 s22, s18, s21
	s_addc_u32 s23, s19, 0
	v_cvt_pk_bf16_f32 v108, v64, v65
	v_cvt_pk_bf16_f32 v109, v66, v67
	v_cvt_pk_bf16_f32 v110, v68, v69
	v_cvt_pk_bf16_f32 v111, v70, v71
	v_cvt_pk_bf16_f32 v112, v72, v73
	v_cvt_pk_bf16_f32 v113, v74, v75
	v_cvt_pk_bf16_f32 v114, v76, v77
	v_cvt_pk_bf16_f32 v115, v78, v79
	global_store_dwordx4 v82, v[108:111], s[22:23]
	global_store_dwordx4 v82, v[112:115], s[22:23] offset:1024
.Lgro0_bend:
	s_mul_i32 s4, s14, 5
	s_add_u32 s13, s13, s4
	s_cmp_lt_u32 s13, 0x2800
	s_cbranch_scc1 .Lgro0_batch
.LBB0_135:
	s_or_b64 exec, exec, s[0:1]
	s_cmp_lt_u32 s45, 3
	s_cbranch_scc1 .LBB0_185
	s_waitcnt vmcnt(0)
	s_barrier
	v_lshrrev_b32_e32 v0, 6, v128
	v_readfirstlane_b32 s20, v0
	s_cmp_lg_u32 s20, 1
	s_cbranch_scc1 .Lxb21_ninv
	buffer_inv sc1
